# FFN-up K-loops: stage LDS-DMA loads issued at the top of each load segment, fragment ds_reads after them
# speedup vs baseline: 1.0042x; 1.0042x over previous
.LBB0_1942:
	s_waitcnt lgkmcnt(0)
	s_add_u32 s26, s8, 0xfff80080
	s_addc_u32 s27, s9, -1
	s_cmp_eq_u32 s53, 28
	s_cselect_b32 s29, s7, s27
	s_cselect_b32 s28, s21, s26
	s_cselect_b32 s27, s19, s52
	s_cselect_b32 s26, s50, s51
	v_lshl_add_u64 v[216:217], s[8:9], 0, v[190:191]
	s_add_i32 m0, s35, 0xc000
	s_nop 0
	global_load_lds_dwordx4 v[216:217], off
	v_lshl_add_u64 v[216:217], s[8:9], 0, v[192:193]
	s_add_i32 m0, s35, 0xe000
	s_nop 0
	global_load_lds_dwordx4 v[216:217], off
	ds_read_b128 v[130:133], v200
	ds_read_b128 v[134:137], v200 offset:1024
	ds_read_b128 v[138:141], v200 offset:2048
	ds_read_b128 v[142:145], v200 offset:3072
	ds_read_b128 v[146:149], v201
	ds_read_b128 v[150:153], v201 offset:1024
	ds_read_b128 v[154:157], v201 offset:2048
	ds_read_b128 v[158:161], v201 offset:3072
	ds_read_b128 v[162:165], v202
	ds_read_b128 v[166:169], v202 offset:1024
	ds_read_b128 v[170:173], v202 offset:2048
	ds_read_b128 v[174:177], v202 offset:3072
	ds_read_b128 v[178:181], v202 offset:4096
	ds_read_b128 v[204:207], v202 offset:5120
	ds_read_b128 v[208:211], v202 offset:6144
	ds_read_b128 v[212:215], v202 offset:7168
	s_waitcnt vmcnt(8)
	s_waitcnt lgkmcnt(0)
	s_barrier
	s_setprio 1
	s_waitcnt lgkmcnt(0)
	v_mfma_f32_16x16x32_bf16 v[126:129], v[130:133], v[162:165], v[126:129]
	v_mfma_f32_16x16x32_bf16 v[122:125], v[138:141], v[162:165], v[122:125]
	v_mfma_f32_16x16x32_bf16 v[118:121], v[130:133], v[170:173], v[118:121]
	v_mfma_f32_16x16x32_bf16 v[110:113], v[138:141], v[170:173], v[110:113]
	v_mfma_f32_16x16x32_bf16 v[102:105], v[130:133], v[178:181], v[102:105]
	v_mfma_f32_16x16x32_bf16 v[94:97], v[138:141], v[178:181], v[94:97]
	v_mfma_f32_16x16x32_bf16 v[86:89], v[130:133], v[208:211], v[86:89]
	v_mfma_f32_16x16x32_bf16 v[78:81], v[138:141], v[208:211], v[78:81]
	v_mfma_f32_16x16x32_bf16 v[126:129], v[134:137], v[166:169], v[126:129]
	v_mfma_f32_16x16x32_bf16 v[122:125], v[142:145], v[166:169], v[122:125]
	v_mfma_f32_16x16x32_bf16 v[118:121], v[134:137], v[174:177], v[118:121]
	v_mfma_f32_16x16x32_bf16 v[110:113], v[142:145], v[174:177], v[110:113]
	v_mfma_f32_16x16x32_bf16 v[102:105], v[134:137], v[204:207], v[102:105]
	v_mfma_f32_16x16x32_bf16 v[94:97], v[142:145], v[204:207], v[94:97]
	v_mfma_f32_16x16x32_bf16 v[86:89], v[134:137], v[212:215], v[86:89]
	v_mfma_f32_16x16x32_bf16 v[78:81], v[142:145], v[212:215], v[78:81]
	s_setprio 0
	s_setprio 1
	v_mfma_f32_16x16x32_bf16 v[114:117], v[146:149], v[162:165], v[114:117]
	v_mfma_f32_16x16x32_bf16 v[106:109], v[154:157], v[162:165], v[106:109]
	v_mfma_f32_16x16x32_bf16 v[98:101], v[146:149], v[170:173], v[98:101]
	v_mfma_f32_16x16x32_bf16 v[90:93], v[154:157], v[170:173], v[90:93]
	v_mfma_f32_16x16x32_bf16 v[82:85], v[146:149], v[178:181], v[82:85]
	v_mfma_f32_16x16x32_bf16 v[74:77], v[154:157], v[178:181], v[74:77]
	v_mfma_f32_16x16x32_bf16 v[70:73], v[146:149], v[208:211], v[70:73]
	v_mfma_f32_16x16x32_bf16 v[66:69], v[154:157], v[208:211], v[66:69]
	v_mfma_f32_16x16x32_bf16 v[114:117], v[150:153], v[166:169], v[114:117]
	v_mfma_f32_16x16x32_bf16 v[106:109], v[158:161], v[166:169], v[106:109]
	v_mfma_f32_16x16x32_bf16 v[98:101], v[150:153], v[174:177], v[98:101]
	v_mfma_f32_16x16x32_bf16 v[90:93], v[158:161], v[174:177], v[90:93]
	v_mfma_f32_16x16x32_bf16 v[82:85], v[150:153], v[204:207], v[82:85]
	v_mfma_f32_16x16x32_bf16 v[74:77], v[158:161], v[204:207], v[74:77]
	v_mfma_f32_16x16x32_bf16 v[70:73], v[150:153], v[212:215], v[70:73]
	v_mfma_f32_16x16x32_bf16 v[66:69], v[158:161], v[212:215], v[66:69]
	s_setprio 0
	s_barrier
	s_add_i32 s54, s45, s31
	v_lshl_add_u64 v[216:217], s[26:27], 0, v[186:187]
	s_mov_b32 m0, s54
	s_nop 0
	global_load_lds_dwordx4 v[216:217], off
	s_add_i32 m0, s54, 0x2000
	s_add_u32 s54, s26, 0x80000
	v_lshl_add_u64 v[218:219], s[26:27], 0, v[182:183]
	s_addc_u32 s55, s27, 0
	s_add_i32 s56, s46, s31
	global_load_lds_dwordx4 v[218:219], off
	v_lshl_add_u64 v[220:221], s[54:55], 0, v[186:187]
	s_mov_b32 m0, s56
	v_lshl_add_u64 v[222:223], s[28:29], 0, v[184:185]
	global_load_lds_dwordx4 v[220:221], off
	v_lshl_add_u64 v[220:221], s[54:55], 0, v[182:183]
	s_add_i32 m0, s56, 0x2000
	s_nop 0
	global_load_lds_dwordx4 v[220:221], off
	v_lshl_add_u64 v[220:221], s[28:29], 0, v[188:189]
	s_mov_b32 m0, s35
	s_nop 0
	global_load_lds_dwordx4 v[220:221], off
	s_mov_b32 m0, s36
	s_nop 0
	global_load_lds_dwordx4 v[222:223], off
	ds_read_b128 v[162:165], v202 offset:16384
	ds_read_b128 v[166:169], v202 offset:17408
	ds_read_b128 v[170:173], v202 offset:18432
	ds_read_b128 v[174:177], v202 offset:19456
	ds_read_b128 v[178:181], v202 offset:20480
	ds_read_b128 v[204:207], v202 offset:21504
	ds_read_b128 v[208:211], v202 offset:22528
	ds_read_b128 v[212:215], v202 offset:23552
	s_waitcnt vmcnt(8)
	s_waitcnt lgkmcnt(0)
	s_barrier
	s_setprio 1
	s_waitcnt lgkmcnt(0)
	v_mfma_f32_16x16x32_bf16 v[62:65], v[130:133], v[162:165], v[62:65]
	v_mfma_f32_16x16x32_bf16 v[58:61], v[138:141], v[162:165], v[58:61]
	v_mfma_f32_16x16x32_bf16 v[54:57], v[130:133], v[170:173], v[54:57]
	v_mfma_f32_16x16x32_bf16 v[46:49], v[138:141], v[170:173], v[46:49]
	v_mfma_f32_16x16x32_bf16 v[38:41], v[130:133], v[178:181], v[38:41]
	v_mfma_f32_16x16x32_bf16 v[30:33], v[138:141], v[178:181], v[30:33]
	v_mfma_f32_16x16x32_bf16 v[22:25], v[130:133], v[208:211], v[22:25]
	v_mfma_f32_16x16x32_bf16 v[14:17], v[138:141], v[208:211], v[14:17]
	v_mfma_f32_16x16x32_bf16 v[62:65], v[134:137], v[166:169], v[62:65]
	v_mfma_f32_16x16x32_bf16 v[58:61], v[142:145], v[166:169], v[58:61]
	v_mfma_f32_16x16x32_bf16 v[54:57], v[134:137], v[174:177], v[54:57]
	v_mfma_f32_16x16x32_bf16 v[46:49], v[142:145], v[174:177], v[46:49]
	v_mfma_f32_16x16x32_bf16 v[38:41], v[134:137], v[204:207], v[38:41]
	v_mfma_f32_16x16x32_bf16 v[30:33], v[142:145], v[204:207], v[30:33]
	v_mfma_f32_16x16x32_bf16 v[22:25], v[134:137], v[212:215], v[22:25]
	v_mfma_f32_16x16x32_bf16 v[14:17], v[142:145], v[212:215], v[14:17]
	s_setprio 0
	s_setprio 1
	v_mfma_f32_16x16x32_bf16 v[50:53], v[146:149], v[162:165], v[50:53]
	v_mfma_f32_16x16x32_bf16 v[42:45], v[154:157], v[162:165], v[42:45]
	v_mfma_f32_16x16x32_bf16 v[34:37], v[146:149], v[170:173], v[34:37]
	v_mfma_f32_16x16x32_bf16 v[26:29], v[154:157], v[170:173], v[26:29]
	v_mfma_f32_16x16x32_bf16 v[18:21], v[146:149], v[178:181], v[18:21]
	v_mfma_f32_16x16x32_bf16 v[10:13], v[154:157], v[178:181], v[10:13]
	v_mfma_f32_16x16x32_bf16 v[6:9], v[146:149], v[208:211], v[6:9]
	v_mfma_f32_16x16x32_bf16 v[2:5], v[154:157], v[208:211], v[2:5]
	v_mfma_f32_16x16x32_bf16 v[50:53], v[150:153], v[166:169], v[50:53]
	v_mfma_f32_16x16x32_bf16 v[42:45], v[158:161], v[166:169], v[42:45]
	v_mfma_f32_16x16x32_bf16 v[34:37], v[150:153], v[174:177], v[34:37]
	v_mfma_f32_16x16x32_bf16 v[26:29], v[158:161], v[174:177], v[26:29]
	v_mfma_f32_16x16x32_bf16 v[18:21], v[150:153], v[204:207], v[18:21]
	v_mfma_f32_16x16x32_bf16 v[10:13], v[158:161], v[204:207], v[10:13]
	v_mfma_f32_16x16x32_bf16 v[6:9], v[150:153], v[212:215], v[6:9]
	v_mfma_f32_16x16x32_bf16 v[2:5], v[158:161], v[212:215], v[2:5]
	s_setprio 0
	s_barrier
	s_add_i32 s54, 0, 0x18000
	s_add_i32 s55, 0, 0x1c000
	v_add_u32_e32 v142, s54, v199
	v_add_u32_e32 v158, s55, v199
	s_add_u32 s28, s28, 0x80000
	s_addc_u32 s29, s29, 0
	s_mov_b32 m0, s37
	v_lshl_add_u64 v[224:225], s[28:29], 0, v[188:189]
	global_load_lds_dwordx4 v[224:225], off
	v_lshl_add_u64 v[224:225], s[28:29], 0, v[184:185]
	s_mov_b32 m0, s38
	s_nop 0
	global_load_lds_dwordx4 v[224:225], off
	ds_read_b128 v[130:133], v142
	ds_read_b128 v[134:137], v142 offset:1024
	ds_read_b128 v[138:141], v142 offset:2048
	ds_read_b128 v[142:145], v142 offset:3072
	ds_read_b128 v[146:149], v158
	ds_read_b128 v[150:153], v158 offset:1024
	ds_read_b128 v[154:157], v158 offset:2048
	ds_read_b128 v[158:161], v158 offset:3072
	ds_read_b128 v[162:165], v202 offset:32768
	ds_read_b128 v[166:169], v202 offset:33792
	ds_read_b128 v[170:173], v202 offset:34816
	ds_read_b128 v[174:177], v202 offset:35840
	ds_read_b128 v[178:181], v202 offset:36864
	ds_read_b128 v[204:207], v202 offset:37888
	ds_read_b128 v[208:211], v202 offset:38912
	ds_read_b128 v[212:215], v202 offset:39936
	s_waitcnt vmcnt(8)
	s_waitcnt lgkmcnt(0)
	s_barrier
	s_setprio 1
	s_waitcnt lgkmcnt(0)
	v_mfma_f32_16x16x32_bf16 v[126:129], v[130:133], v[162:165], v[126:129]
	v_mfma_f32_16x16x32_bf16 v[122:125], v[138:141], v[162:165], v[122:125]
	v_mfma_f32_16x16x32_bf16 v[118:121], v[130:133], v[170:173], v[118:121]
	v_mfma_f32_16x16x32_bf16 v[110:113], v[138:141], v[170:173], v[110:113]
	v_mfma_f32_16x16x32_bf16 v[102:105], v[130:133], v[178:181], v[102:105]
	v_mfma_f32_16x16x32_bf16 v[94:97], v[138:141], v[178:181], v[94:97]
	v_mfma_f32_16x16x32_bf16 v[86:89], v[130:133], v[208:211], v[86:89]
	v_mfma_f32_16x16x32_bf16 v[78:81], v[138:141], v[208:211], v[78:81]
	v_mfma_f32_16x16x32_bf16 v[126:129], v[134:137], v[166:169], v[126:129]
	v_mfma_f32_16x16x32_bf16 v[122:125], v[142:145], v[166:169], v[122:125]
	v_mfma_f32_16x16x32_bf16 v[118:121], v[134:137], v[174:177], v[118:121]
	v_mfma_f32_16x16x32_bf16 v[110:113], v[142:145], v[174:177], v[110:113]
	v_mfma_f32_16x16x32_bf16 v[102:105], v[134:137], v[204:207], v[102:105]
	v_mfma_f32_16x16x32_bf16 v[94:97], v[142:145], v[204:207], v[94:97]
	v_mfma_f32_16x16x32_bf16 v[86:89], v[134:137], v[212:215], v[86:89]
	v_mfma_f32_16x16x32_bf16 v[78:81], v[142:145], v[212:215], v[78:81]
	s_setprio 0
	s_setprio 1
	v_mfma_f32_16x16x32_bf16 v[114:117], v[146:149], v[162:165], v[114:117]
	v_mfma_f32_16x16x32_bf16 v[106:109], v[154:157], v[162:165], v[106:109]
	v_mfma_f32_16x16x32_bf16 v[98:101], v[146:149], v[170:173], v[98:101]
	v_mfma_f32_16x16x32_bf16 v[90:93], v[154:157], v[170:173], v[90:93]
	v_mfma_f32_16x16x32_bf16 v[82:85], v[146:149], v[178:181], v[82:85]
	v_mfma_f32_16x16x32_bf16 v[74:77], v[154:157], v[178:181], v[74:77]
	v_mfma_f32_16x16x32_bf16 v[70:73], v[146:149], v[208:211], v[70:73]
	v_mfma_f32_16x16x32_bf16 v[66:69], v[154:157], v[208:211], v[66:69]
	v_mfma_f32_16x16x32_bf16 v[114:117], v[150:153], v[166:169], v[114:117]
	v_mfma_f32_16x16x32_bf16 v[106:109], v[158:161], v[166:169], v[106:109]
	v_mfma_f32_16x16x32_bf16 v[98:101], v[150:153], v[174:177], v[98:101]
	v_mfma_f32_16x16x32_bf16 v[90:93], v[158:161], v[174:177], v[90:93]
	v_mfma_f32_16x16x32_bf16 v[82:85], v[150:153], v[204:207], v[82:85]
	v_mfma_f32_16x16x32_bf16 v[74:77], v[158:161], v[204:207], v[74:77]
	v_mfma_f32_16x16x32_bf16 v[70:73], v[150:153], v[212:215], v[70:73]
	v_mfma_f32_16x16x32_bf16 v[66:69], v[158:161], v[212:215], v[66:69]
	s_setprio 0
	s_barrier
	s_add_i32 s28, s54, s31
	v_lshl_add_u64 v[216:217], v[216:217], 0, s[12:13]
	s_mov_b32 m0, s28
	s_nop 0
	global_load_lds_dwordx4 v[216:217], off
	s_add_i32 m0, s28, 0x2000
	s_add_u32 s26, s26, 0x80080
	v_lshl_add_u64 v[216:217], v[218:219], 0, s[12:13]
	s_addc_u32 s27, s27, 0
	s_add_i32 s28, s55, s31
	global_load_lds_dwordx4 v[216:217], off
	v_lshl_add_u64 v[216:217], s[26:27], 0, v[186:187]
	s_mov_b32 m0, s28
	s_nop 0
	global_load_lds_dwordx4 v[216:217], off
	v_lshl_add_u64 v[216:217], s[26:27], 0, v[182:183]
	s_add_i32 m0, s28, 0x2000
	s_nop 0
	global_load_lds_dwordx4 v[216:217], off
	v_lshl_add_u64 v[216:217], v[220:221], 0, s[12:13]
	s_mov_b32 m0, s42
	s_nop 0
	global_load_lds_dwordx4 v[216:217], off
	v_lshl_add_u64 v[216:217], v[222:223], 0, s[12:13]
	s_mov_b32 m0, s43
	s_nop 0
	global_load_lds_dwordx4 v[216:217], off
	ds_read_b128 v[162:165], v202 offset:49152
	ds_read_b128 v[166:169], v202 offset:50176
	ds_read_b128 v[170:173], v202 offset:51200
	ds_read_b128 v[174:177], v202 offset:52224
	ds_read_b128 v[178:181], v202 offset:53248
	ds_read_b128 v[204:207], v202 offset:54272
	ds_read_b128 v[208:211], v202 offset:55296
	ds_read_b128 v[212:215], v202 offset:56320
	s_waitcnt vmcnt(8)
	s_waitcnt lgkmcnt(0)
	s_barrier
	s_setprio 1
	s_waitcnt lgkmcnt(0)
	v_mfma_f32_16x16x32_bf16 v[62:65], v[130:133], v[162:165], v[62:65]
	v_mfma_f32_16x16x32_bf16 v[58:61], v[138:141], v[162:165], v[58:61]
	v_mfma_f32_16x16x32_bf16 v[54:57], v[130:133], v[170:173], v[54:57]
	v_mfma_f32_16x16x32_bf16 v[46:49], v[138:141], v[170:173], v[46:49]
	v_mfma_f32_16x16x32_bf16 v[38:41], v[130:133], v[178:181], v[38:41]
	v_mfma_f32_16x16x32_bf16 v[30:33], v[138:141], v[178:181], v[30:33]
	v_mfma_f32_16x16x32_bf16 v[22:25], v[130:133], v[208:211], v[22:25]
	v_mfma_f32_16x16x32_bf16 v[14:17], v[138:141], v[208:211], v[14:17]
	v_mfma_f32_16x16x32_bf16 v[62:65], v[134:137], v[166:169], v[62:65]
	v_mfma_f32_16x16x32_bf16 v[58:61], v[142:145], v[166:169], v[58:61]
	v_mfma_f32_16x16x32_bf16 v[54:57], v[134:137], v[174:177], v[54:57]
	v_mfma_f32_16x16x32_bf16 v[46:49], v[142:145], v[174:177], v[46:49]
	v_mfma_f32_16x16x32_bf16 v[38:41], v[134:137], v[204:207], v[38:41]
	v_mfma_f32_16x16x32_bf16 v[30:33], v[142:145], v[204:207], v[30:33]
	v_mfma_f32_16x16x32_bf16 v[22:25], v[134:137], v[212:215], v[22:25]
	v_mfma_f32_16x16x32_bf16 v[14:17], v[142:145], v[212:215], v[14:17]
	s_setprio 0
	s_setprio 1
	v_mfma_f32_16x16x32_bf16 v[50:53], v[146:149], v[162:165], v[50:53]
	v_mfma_f32_16x16x32_bf16 v[42:45], v[154:157], v[162:165], v[42:45]
	v_mfma_f32_16x16x32_bf16 v[34:37], v[146:149], v[170:173], v[34:37]
	v_mfma_f32_16x16x32_bf16 v[26:29], v[154:157], v[170:173], v[26:29]
	v_mfma_f32_16x16x32_bf16 v[18:21], v[146:149], v[178:181], v[18:21]
	v_mfma_f32_16x16x32_bf16 v[10:13], v[154:157], v[178:181], v[10:13]
	v_mfma_f32_16x16x32_bf16 v[6:9], v[146:149], v[208:211], v[6:9]
	v_mfma_f32_16x16x32_bf16 v[2:5], v[154:157], v[208:211], v[2:5]
	v_mfma_f32_16x16x32_bf16 v[50:53], v[150:153], v[166:169], v[50:53]
	v_mfma_f32_16x16x32_bf16 v[42:45], v[158:161], v[166:169], v[42:45]
	v_mfma_f32_16x16x32_bf16 v[34:37], v[150:153], v[174:177], v[34:37]
	v_mfma_f32_16x16x32_bf16 v[26:29], v[158:161], v[174:177], v[26:29]
	v_mfma_f32_16x16x32_bf16 v[18:21], v[150:153], v[204:207], v[18:21]
	v_mfma_f32_16x16x32_bf16 v[10:13], v[158:161], v[204:207], v[10:13]
	v_mfma_f32_16x16x32_bf16 v[6:9], v[150:153], v[212:215], v[6:9]
	v_mfma_f32_16x16x32_bf16 v[2:5], v[158:161], v[212:215], v[2:5]
	s_setprio 0
	s_barrier
	s_add_i32 s53, s53, 2
	s_add_u32 s8, s8, 0x100
	s_addc_u32 s9, s9, 0
	s_add_u32 s51, s51, 0x100
	s_addc_u32 s52, s52, 0
	s_cmp_gt_u32 s53, 29
	s_cbranch_scc0 .LBB0_1942
	s_and_b64 vcc, exec, s[14:15]
	s_cbranch_vccz .LBB0_1945
	s_barrier

.LBB0_3201:
	s_waitcnt lgkmcnt(0)
	s_add_u32 s40, s8, 0xfff80080
	s_addc_u32 s41, s9, -1
	s_cmp_eq_u32 s66, 28
	s_cselect_b32 s43, s7, s41
	s_cselect_b32 s42, s35, s40
	s_cselect_b32 s41, s31, s65
	s_cselect_b32 s40, s63, s64
	v_lshl_add_u64 v[216:217], s[8:9], 0, v[138:139]
	s_add_i32 m0, s46, 0xc000
	s_nop 0
	global_load_lds_dwordx4 v[216:217], off
	v_lshl_add_u64 v[216:217], s[8:9], 0, v[140:141]
	s_add_i32 m0, s46, 0xe000
	s_nop 0
	global_load_lds_dwordx4 v[216:217], off
	ds_read_b128 v[146:149], v164
	ds_read_b128 v[150:153], v164 offset:1024
	ds_read_b128 v[154:157], v164 offset:2048
	ds_read_b128 v[158:161], v164 offset:3072
	ds_read_b128 v[168:171], v165
	ds_read_b128 v[172:175], v165 offset:1024
	ds_read_b128 v[176:179], v165 offset:2048
	ds_read_b128 v[180:183], v165 offset:3072
	ds_read_b128 v[184:187], v166
	ds_read_b128 v[188:191], v166 offset:1024
	ds_read_b128 v[192:195], v166 offset:2048
	ds_read_b128 v[196:199], v166 offset:3072
	ds_read_b128 v[200:203], v166 offset:4096
	ds_read_b128 v[204:207], v166 offset:5120
	ds_read_b128 v[208:211], v166 offset:6144
	ds_read_b128 v[212:215], v166 offset:7168
	s_waitcnt vmcnt(8)
	s_waitcnt lgkmcnt(0)
	s_barrier
	s_setprio 1
	s_waitcnt lgkmcnt(0)
	v_mfma_f32_16x16x32_bf16 v[126:129], v[146:149], v[184:187], v[126:129]
	v_mfma_f32_16x16x32_bf16 v[122:125], v[154:157], v[184:187], v[122:125]
	v_mfma_f32_16x16x32_bf16 v[118:121], v[146:149], v[192:195], v[118:121]
	v_mfma_f32_16x16x32_bf16 v[110:113], v[154:157], v[192:195], v[110:113]
	v_mfma_f32_16x16x32_bf16 v[102:105], v[146:149], v[200:203], v[102:105]
	v_mfma_f32_16x16x32_bf16 v[94:97], v[154:157], v[200:203], v[94:97]
	v_mfma_f32_16x16x32_bf16 v[86:89], v[146:149], v[208:211], v[86:89]
	v_mfma_f32_16x16x32_bf16 v[78:81], v[154:157], v[208:211], v[78:81]
	v_mfma_f32_16x16x32_bf16 v[126:129], v[150:153], v[188:191], v[126:129]
	v_mfma_f32_16x16x32_bf16 v[122:125], v[158:161], v[188:191], v[122:125]
	v_mfma_f32_16x16x32_bf16 v[118:121], v[150:153], v[196:199], v[118:121]
	v_mfma_f32_16x16x32_bf16 v[110:113], v[158:161], v[196:199], v[110:113]
	v_mfma_f32_16x16x32_bf16 v[102:105], v[150:153], v[204:207], v[102:105]
	v_mfma_f32_16x16x32_bf16 v[94:97], v[158:161], v[204:207], v[94:97]
	v_mfma_f32_16x16x32_bf16 v[86:89], v[150:153], v[212:215], v[86:89]
	v_mfma_f32_16x16x32_bf16 v[78:81], v[158:161], v[212:215], v[78:81]
	s_setprio 0
	s_setprio 1
	v_mfma_f32_16x16x32_bf16 v[114:117], v[168:171], v[184:187], v[114:117]
	v_mfma_f32_16x16x32_bf16 v[106:109], v[176:179], v[184:187], v[106:109]
	v_mfma_f32_16x16x32_bf16 v[98:101], v[168:171], v[192:195], v[98:101]
	v_mfma_f32_16x16x32_bf16 v[90:93], v[176:179], v[192:195], v[90:93]
	v_mfma_f32_16x16x32_bf16 v[82:85], v[168:171], v[200:203], v[82:85]
	v_mfma_f32_16x16x32_bf16 v[74:77], v[176:179], v[200:203], v[74:77]
	v_mfma_f32_16x16x32_bf16 v[70:73], v[168:171], v[208:211], v[70:73]
	v_mfma_f32_16x16x32_bf16 v[66:69], v[176:179], v[208:211], v[66:69]
	v_mfma_f32_16x16x32_bf16 v[114:117], v[172:175], v[188:191], v[114:117]
	v_mfma_f32_16x16x32_bf16 v[106:109], v[180:183], v[188:191], v[106:109]
	v_mfma_f32_16x16x32_bf16 v[98:101], v[172:175], v[196:199], v[98:101]
	v_mfma_f32_16x16x32_bf16 v[90:93], v[180:183], v[196:199], v[90:93]
	v_mfma_f32_16x16x32_bf16 v[82:85], v[172:175], v[204:207], v[82:85]
	v_mfma_f32_16x16x32_bf16 v[74:77], v[180:183], v[204:207], v[74:77]
	v_mfma_f32_16x16x32_bf16 v[70:73], v[172:175], v[212:215], v[70:73]
	v_mfma_f32_16x16x32_bf16 v[66:69], v[180:183], v[212:215], v[66:69]
	s_setprio 0
	s_barrier
	s_add_i32 s67, s56, s33
	v_lshl_add_u64 v[216:217], s[40:41], 0, v[134:135]
	s_mov_b32 m0, s67
	s_nop 0
	global_load_lds_dwordx4 v[216:217], off
	s_add_i32 m0, s67, 0x2000
	s_add_u32 s68, s40, 0x80000
	v_lshl_add_u64 v[218:219], s[40:41], 0, v[130:131]
	s_addc_u32 s69, s41, 0
	s_add_i32 s67, s57, s33
	global_load_lds_dwordx4 v[218:219], off
	v_lshl_add_u64 v[220:221], s[68:69], 0, v[134:135]
	s_mov_b32 m0, s67
	v_lshl_add_u64 v[222:223], s[42:43], 0, v[132:133]
	global_load_lds_dwordx4 v[220:221], off
	v_lshl_add_u64 v[220:221], s[68:69], 0, v[130:131]
	s_add_i32 m0, s67, 0x2000
	s_nop 0
	global_load_lds_dwordx4 v[220:221], off
	v_lshl_add_u64 v[220:221], s[42:43], 0, v[136:137]
	s_mov_b32 m0, s46
	s_nop 0
	global_load_lds_dwordx4 v[220:221], off
	s_mov_b32 m0, s47
	s_nop 0
	global_load_lds_dwordx4 v[222:223], off
	ds_read_b128 v[184:187], v166 offset:16384
	ds_read_b128 v[188:191], v166 offset:17408
	ds_read_b128 v[192:195], v166 offset:18432
	ds_read_b128 v[196:199], v166 offset:19456
	ds_read_b128 v[200:203], v166 offset:20480
	ds_read_b128 v[204:207], v166 offset:21504
	ds_read_b128 v[208:211], v166 offset:22528
	ds_read_b128 v[212:215], v166 offset:23552
	s_waitcnt vmcnt(8)
	s_waitcnt lgkmcnt(0)
	s_barrier
	s_setprio 1
	s_waitcnt lgkmcnt(0)
	v_mfma_f32_16x16x32_bf16 v[62:65], v[146:149], v[184:187], v[62:65]
	v_mfma_f32_16x16x32_bf16 v[58:61], v[154:157], v[184:187], v[58:61]
	v_mfma_f32_16x16x32_bf16 v[54:57], v[146:149], v[192:195], v[54:57]
	v_mfma_f32_16x16x32_bf16 v[46:49], v[154:157], v[192:195], v[46:49]
	v_mfma_f32_16x16x32_bf16 v[38:41], v[146:149], v[200:203], v[38:41]
	v_mfma_f32_16x16x32_bf16 v[30:33], v[154:157], v[200:203], v[30:33]
	v_mfma_f32_16x16x32_bf16 v[22:25], v[146:149], v[208:211], v[22:25]
	v_mfma_f32_16x16x32_bf16 v[14:17], v[154:157], v[208:211], v[14:17]
	v_mfma_f32_16x16x32_bf16 v[62:65], v[150:153], v[188:191], v[62:65]
	v_mfma_f32_16x16x32_bf16 v[58:61], v[158:161], v[188:191], v[58:61]
	v_mfma_f32_16x16x32_bf16 v[54:57], v[150:153], v[196:199], v[54:57]
	v_mfma_f32_16x16x32_bf16 v[46:49], v[158:161], v[196:199], v[46:49]
	v_mfma_f32_16x16x32_bf16 v[38:41], v[150:153], v[204:207], v[38:41]
	v_mfma_f32_16x16x32_bf16 v[30:33], v[158:161], v[204:207], v[30:33]
	v_mfma_f32_16x16x32_bf16 v[22:25], v[150:153], v[212:215], v[22:25]
	v_mfma_f32_16x16x32_bf16 v[14:17], v[158:161], v[212:215], v[14:17]
	s_setprio 0
	s_setprio 1
	v_mfma_f32_16x16x32_bf16 v[50:53], v[168:171], v[184:187], v[50:53]
	v_mfma_f32_16x16x32_bf16 v[42:45], v[176:179], v[184:187], v[42:45]
	v_mfma_f32_16x16x32_bf16 v[34:37], v[168:171], v[192:195], v[34:37]
	v_mfma_f32_16x16x32_bf16 v[26:29], v[176:179], v[192:195], v[26:29]
	v_mfma_f32_16x16x32_bf16 v[18:21], v[168:171], v[200:203], v[18:21]
	v_mfma_f32_16x16x32_bf16 v[10:13], v[176:179], v[200:203], v[10:13]
	v_mfma_f32_16x16x32_bf16 v[6:9], v[168:171], v[208:211], v[6:9]
	v_mfma_f32_16x16x32_bf16 v[2:5], v[176:179], v[208:211], v[2:5]
	v_mfma_f32_16x16x32_bf16 v[50:53], v[172:175], v[188:191], v[50:53]
	v_mfma_f32_16x16x32_bf16 v[42:45], v[180:183], v[188:191], v[42:45]
	v_mfma_f32_16x16x32_bf16 v[34:37], v[172:175], v[196:199], v[34:37]
	v_mfma_f32_16x16x32_bf16 v[26:29], v[180:183], v[196:199], v[26:29]
	v_mfma_f32_16x16x32_bf16 v[18:21], v[172:175], v[204:207], v[18:21]
	v_mfma_f32_16x16x32_bf16 v[10:13], v[180:183], v[204:207], v[10:13]
	v_mfma_f32_16x16x32_bf16 v[6:9], v[172:175], v[212:215], v[6:9]
	v_mfma_f32_16x16x32_bf16 v[2:5], v[180:183], v[212:215], v[2:5]
	s_setprio 0
	s_barrier
	s_add_i32 s67, 0, 0x18000
	s_add_i32 s68, 0, 0x1c000
	v_add_u32_e32 v158, s67, v163
	v_add_u32_e32 v180, s68, v163
	s_add_u32 s42, s42, 0x80000
	s_addc_u32 s43, s43, 0
	s_mov_b32 m0, s48
	v_lshl_add_u64 v[224:225], s[42:43], 0, v[136:137]
	global_load_lds_dwordx4 v[224:225], off
	v_lshl_add_u64 v[224:225], s[42:43], 0, v[132:133]
	s_mov_b32 m0, s49
	s_nop 0
	global_load_lds_dwordx4 v[224:225], off
	ds_read_b128 v[146:149], v158
	ds_read_b128 v[150:153], v158 offset:1024
	ds_read_b128 v[154:157], v158 offset:2048
	ds_read_b128 v[158:161], v158 offset:3072
	ds_read_b128 v[168:171], v180
	ds_read_b128 v[172:175], v180 offset:1024
	ds_read_b128 v[176:179], v180 offset:2048
	ds_read_b128 v[180:183], v180 offset:3072
	ds_read_b128 v[184:187], v166 offset:32768
	ds_read_b128 v[188:191], v166 offset:33792
	ds_read_b128 v[192:195], v166 offset:34816
	ds_read_b128 v[196:199], v166 offset:35840
	ds_read_b128 v[200:203], v166 offset:36864
	ds_read_b128 v[204:207], v166 offset:37888
	ds_read_b128 v[208:211], v166 offset:38912
	ds_read_b128 v[212:215], v166 offset:39936
	s_waitcnt vmcnt(8)
	s_waitcnt lgkmcnt(0)
	s_barrier
	s_setprio 1
	s_waitcnt lgkmcnt(0)
	v_mfma_f32_16x16x32_bf16 v[126:129], v[146:149], v[184:187], v[126:129]
	v_mfma_f32_16x16x32_bf16 v[122:125], v[154:157], v[184:187], v[122:125]
	v_mfma_f32_16x16x32_bf16 v[118:121], v[146:149], v[192:195], v[118:121]
	v_mfma_f32_16x16x32_bf16 v[110:113], v[154:157], v[192:195], v[110:113]
	v_mfma_f32_16x16x32_bf16 v[102:105], v[146:149], v[200:203], v[102:105]
	v_mfma_f32_16x16x32_bf16 v[94:97], v[154:157], v[200:203], v[94:97]
	v_mfma_f32_16x16x32_bf16 v[86:89], v[146:149], v[208:211], v[86:89]
	v_mfma_f32_16x16x32_bf16 v[78:81], v[154:157], v[208:211], v[78:81]
	v_mfma_f32_16x16x32_bf16 v[126:129], v[150:153], v[188:191], v[126:129]
	v_mfma_f32_16x16x32_bf16 v[122:125], v[158:161], v[188:191], v[122:125]
	v_mfma_f32_16x16x32_bf16 v[118:121], v[150:153], v[196:199], v[118:121]
	v_mfma_f32_16x16x32_bf16 v[110:113], v[158:161], v[196:199], v[110:113]
	v_mfma_f32_16x16x32_bf16 v[102:105], v[150:153], v[204:207], v[102:105]
	v_mfma_f32_16x16x32_bf16 v[94:97], v[158:161], v[204:207], v[94:97]
	v_mfma_f32_16x16x32_bf16 v[86:89], v[150:153], v[212:215], v[86:89]
	v_mfma_f32_16x16x32_bf16 v[78:81], v[158:161], v[212:215], v[78:81]
	s_setprio 0
	s_setprio 1
	v_mfma_f32_16x16x32_bf16 v[114:117], v[168:171], v[184:187], v[114:117]
	v_mfma_f32_16x16x32_bf16 v[106:109], v[176:179], v[184:187], v[106:109]
	v_mfma_f32_16x16x32_bf16 v[98:101], v[168:171], v[192:195], v[98:101]
	v_mfma_f32_16x16x32_bf16 v[90:93], v[176:179], v[192:195], v[90:93]
	v_mfma_f32_16x16x32_bf16 v[82:85], v[168:171], v[200:203], v[82:85]
	v_mfma_f32_16x16x32_bf16 v[74:77], v[176:179], v[200:203], v[74:77]
	v_mfma_f32_16x16x32_bf16 v[70:73], v[168:171], v[208:211], v[70:73]
	v_mfma_f32_16x16x32_bf16 v[66:69], v[176:179], v[208:211], v[66:69]
	v_mfma_f32_16x16x32_bf16 v[114:117], v[172:175], v[188:191], v[114:117]
	v_mfma_f32_16x16x32_bf16 v[106:109], v[180:183], v[188:191], v[106:109]
	v_mfma_f32_16x16x32_bf16 v[98:101], v[172:175], v[196:199], v[98:101]
	v_mfma_f32_16x16x32_bf16 v[90:93], v[180:183], v[196:199], v[90:93]
	v_mfma_f32_16x16x32_bf16 v[82:85], v[172:175], v[204:207], v[82:85]
	v_mfma_f32_16x16x32_bf16 v[74:77], v[180:183], v[204:207], v[74:77]
	v_mfma_f32_16x16x32_bf16 v[70:73], v[172:175], v[212:215], v[70:73]
	v_mfma_f32_16x16x32_bf16 v[66:69], v[180:183], v[212:215], v[66:69]
	s_setprio 0
	s_barrier
	s_add_i32 s42, s67, s33
	v_lshl_add_u64 v[216:217], v[216:217], 0, s[12:13]
	s_mov_b32 m0, s42
	s_nop 0
	global_load_lds_dwordx4 v[216:217], off
	s_add_i32 m0, s42, 0x2000
	s_add_u32 s40, s40, 0x80080
	v_lshl_add_u64 v[216:217], v[218:219], 0, s[12:13]
	s_addc_u32 s41, s41, 0
	s_add_i32 s42, s68, s33
	global_load_lds_dwordx4 v[216:217], off
	v_lshl_add_u64 v[216:217], s[40:41], 0, v[134:135]
	s_mov_b32 m0, s42
	s_nop 0
	global_load_lds_dwordx4 v[216:217], off
	v_lshl_add_u64 v[216:217], s[40:41], 0, v[130:131]
	s_add_i32 m0, s42, 0x2000
	s_nop 0
	global_load_lds_dwordx4 v[216:217], off
	v_lshl_add_u64 v[216:217], v[220:221], 0, s[12:13]
	s_mov_b32 m0, s53
	s_nop 0
	global_load_lds_dwordx4 v[216:217], off
	v_lshl_add_u64 v[216:217], v[222:223], 0, s[12:13]
	s_mov_b32 m0, s54
	s_nop 0
	global_load_lds_dwordx4 v[216:217], off
	ds_read_b128 v[184:187], v166 offset:49152
	ds_read_b128 v[188:191], v166 offset:50176
	ds_read_b128 v[192:195], v166 offset:51200
	ds_read_b128 v[196:199], v166 offset:52224
	ds_read_b128 v[200:203], v166 offset:53248
	ds_read_b128 v[204:207], v166 offset:54272
	ds_read_b128 v[208:211], v166 offset:55296
	ds_read_b128 v[212:215], v166 offset:56320
	s_waitcnt vmcnt(8)
	s_waitcnt lgkmcnt(0)
	s_barrier
	s_setprio 1
	s_waitcnt lgkmcnt(0)
	v_mfma_f32_16x16x32_bf16 v[62:65], v[146:149], v[184:187], v[62:65]
	v_mfma_f32_16x16x32_bf16 v[58:61], v[154:157], v[184:187], v[58:61]
	v_mfma_f32_16x16x32_bf16 v[54:57], v[146:149], v[192:195], v[54:57]
	v_mfma_f32_16x16x32_bf16 v[46:49], v[154:157], v[192:195], v[46:49]
	v_mfma_f32_16x16x32_bf16 v[38:41], v[146:149], v[200:203], v[38:41]
	v_mfma_f32_16x16x32_bf16 v[30:33], v[154:157], v[200:203], v[30:33]
	v_mfma_f32_16x16x32_bf16 v[22:25], v[146:149], v[208:211], v[22:25]
	v_mfma_f32_16x16x32_bf16 v[14:17], v[154:157], v[208:211], v[14:17]
	v_mfma_f32_16x16x32_bf16 v[62:65], v[150:153], v[188:191], v[62:65]
	v_mfma_f32_16x16x32_bf16 v[58:61], v[158:161], v[188:191], v[58:61]
	v_mfma_f32_16x16x32_bf16 v[54:57], v[150:153], v[196:199], v[54:57]
	v_mfma_f32_16x16x32_bf16 v[46:49], v[158:161], v[196:199], v[46:49]
	v_mfma_f32_16x16x32_bf16 v[38:41], v[150:153], v[204:207], v[38:41]
	v_mfma_f32_16x16x32_bf16 v[30:33], v[158:161], v[204:207], v[30:33]
	v_mfma_f32_16x16x32_bf16 v[22:25], v[150:153], v[212:215], v[22:25]
	v_mfma_f32_16x16x32_bf16 v[14:17], v[158:161], v[212:215], v[14:17]
	s_setprio 0
	s_setprio 1
	v_mfma_f32_16x16x32_bf16 v[50:53], v[168:171], v[184:187], v[50:53]
	v_mfma_f32_16x16x32_bf16 v[42:45], v[176:179], v[184:187], v[42:45]
	v_mfma_f32_16x16x32_bf16 v[34:37], v[168:171], v[192:195], v[34:37]
	v_mfma_f32_16x16x32_bf16 v[26:29], v[176:179], v[192:195], v[26:29]
	v_mfma_f32_16x16x32_bf16 v[18:21], v[168:171], v[200:203], v[18:21]
	v_mfma_f32_16x16x32_bf16 v[10:13], v[176:179], v[200:203], v[10:13]
	v_mfma_f32_16x16x32_bf16 v[6:9], v[168:171], v[208:211], v[6:9]
	v_mfma_f32_16x16x32_bf16 v[2:5], v[176:179], v[208:211], v[2:5]
	v_mfma_f32_16x16x32_bf16 v[50:53], v[172:175], v[188:191], v[50:53]
	v_mfma_f32_16x16x32_bf16 v[42:45], v[180:183], v[188:191], v[42:45]
	v_mfma_f32_16x16x32_bf16 v[34:37], v[172:175], v[196:199], v[34:37]
	v_mfma_f32_16x16x32_bf16 v[26:29], v[180:183], v[196:199], v[26:29]
	v_mfma_f32_16x16x32_bf16 v[18:21], v[172:175], v[204:207], v[18:21]
	v_mfma_f32_16x16x32_bf16 v[10:13], v[180:183], v[204:207], v[10:13]
	v_mfma_f32_16x16x32_bf16 v[6:9], v[172:175], v[212:215], v[6:9]
	v_mfma_f32_16x16x32_bf16 v[2:5], v[180:183], v[212:215], v[2:5]
	s_setprio 0
	s_barrier
	s_add_i32 s66, s66, 2
	s_add_u32 s8, s8, 0x100
	s_addc_u32 s9, s9, 0
	s_add_u32 s64, s64, 0x100
	s_addc_u32 s65, s65, 0
	s_cmp_gt_u32 s66, 29
	s_cbranch_scc0 .LBB0_3201
	s_and_b64 vcc, exec, s[14:15]
	s_cbranch_vccz .LBB0_3204
	s_barrier
